# cmp1 rebalance now guarded: grid below 256 workgroups keeps the original item mapping (robustness only, same work on 512 blocks)
# speedup vs baseline: 1.0050x; 1.0044x over previous
.LBB0_2139:
	s_cmp_lt_i32 s18, s20
	s_cselect_b64 s[2:3], -1, 0
	s_xor_b64 s[0:1], s[0:1], -1
	s_or_b64 s[0:1], s[2:3], s[0:1]
	s_and_b64 vcc, exec, s[0:1]
	s_cbranch_vccnz .LBB0_2142
	v_readlane_b32 s0, v250, 60
	v_readlane_b32 s1, v250, 61
	s_andn2_b64 vcc, exec, s[0:1]
	v_readlane_b32 s0, v251, 21
	v_readlane_b32 s52, v249, 26
	v_readlane_b32 s6, v251, 23
	s_mov_b32 s7, s0
	v_readlane_b32 s53, v249, 27
	v_readlane_b32 s54, v249, 28
	v_readlane_b32 s55, v249, 29
	v_readlane_b32 s56, v249, 30
	v_readlane_b32 s57, v249, 31
	v_readlane_b32 s58, v249, 32
	v_readlane_b32 s59, v249, 33
	v_readlane_b32 s60, v249, 34
	v_readlane_b32 s61, v249, 35
	v_readlane_b32 s62, v249, 36
	v_readlane_b32 s63, v249, 37
	v_readlane_b32 s64, v249, 38
	v_readlane_b32 s65, v249, 39
	v_readlane_b32 s66, v249, 40
	v_readlane_b32 s67, v249, 41
	v_readlane_b32 s1, v251, 22
	v_readlane_b32 s101, v251, 24
	s_nop 0
	s_cmpk_lt_u32 s101, 0x100
	s_cbranch_scc1 .Lc1_orig
	s_add_i32 s100, s7, 0xffffff80
	s_cmp_lt_u32 s100, 0x80
	s_cbranch_scc0 .LBB0_2141
	s_mov_b32 s7, s100
	s_add_i32 s6, s6, 0xffffc000
	s_branch .LBB0_2159
.Lc1_orig:
	s_cbranch_vccz .LBB0_2159
